# SwiGLU epilogues: packed f32 mul/fma (v_pk_*_f32), rs^2 folded into the denominator as x=ss/1024+eps, next group's rsqrt prepared early, 64-bit address step by v_lshl_add_u64
# speedup vs baseline: 1.0073x; 1.0024x over previous
.Lsw9_go:
	s_mov_b64 s[46:47], 0x16000
	s_waitcnt vmcnt(7)
	v_fmamk_f32 v167, v242, 0x3a800000, v194
	v_rsq_f32_e32 v166, v167
	s_nop 0
	v_mul_f32_e32 v166, 0xbfb8aa3b, v166
	v_pk_mul_f32 v[170:171], v[118:119], v[166:167] op_sel_hi:[1,0]
	v_pk_mul_f32 v[172:173], v[120:121], v[166:167] op_sel_hi:[1,0]
	v_pk_mul_f32 v[174:175], v[114:115], v[166:167] op_sel_hi:[1,0]
	v_pk_mul_f32 v[176:177], v[116:117], v[166:167] op_sel_hi:[1,0]
	v_exp_f32_e32 v170, v170
	v_exp_f32_e32 v171, v171
	v_exp_f32_e32 v172, v172
	v_exp_f32_e32 v173, v173
	v_exp_f32_e32 v174, v174
	v_exp_f32_e32 v175, v175
	v_exp_f32_e32 v176, v176
	v_exp_f32_e32 v177, v177
	v_pk_mul_f32 v[118:119], v[118:119], v[126:127]
	v_pk_mul_f32 v[120:121], v[120:121], v[128:129]
	v_pk_mul_f32 v[114:115], v[114:115], v[122:123]
	v_pk_mul_f32 v[116:117], v[116:117], v[124:125]
	v_pk_fma_f32 v[170:171], v[170:171], v[166:167], v[166:167] op_sel:[0,1,1] op_sel_hi:[1,1,1]
	v_pk_fma_f32 v[172:173], v[172:173], v[166:167], v[166:167] op_sel:[0,1,1] op_sel_hi:[1,1,1]
	v_pk_fma_f32 v[174:175], v[174:175], v[166:167], v[166:167] op_sel:[0,1,1] op_sel_hi:[1,1,1]
	v_pk_fma_f32 v[176:177], v[176:177], v[166:167], v[166:167] op_sel:[0,1,1] op_sel_hi:[1,1,1]
	v_rcp_f32_e32 v170, v170
	v_rcp_f32_e32 v171, v171
	v_rcp_f32_e32 v172, v172
	v_rcp_f32_e32 v173, v173
	v_rcp_f32_e32 v174, v174
	v_rcp_f32_e32 v175, v175
	v_rcp_f32_e32 v176, v176
	v_rcp_f32_e32 v177, v177
	s_waitcnt vmcnt(6)
	v_fmamk_f32 v179, v243, 0x3a800000, v194
	v_rsq_f32_e32 v178, v179
	s_nop 0
	v_mul_f32_e32 v178, 0xbfb8aa3b, v178
	v_pk_mul_f32 v[118:119], v[118:119], v[170:171]
	v_pk_mul_f32 v[120:121], v[120:121], v[172:173]
	v_pk_mul_f32 v[114:115], v[114:115], v[174:175]
	v_pk_mul_f32 v[116:117], v[116:117], v[176:177]
	v_cvt_pk_bf16_f32 v184, v118, v119
	v_cvt_pk_bf16_f32 v185, v120, v121
	v_cvt_pk_bf16_f32 v186, v114, v115
	v_cvt_pk_bf16_f32 v187, v116, v117
	global_store_dwordx4 v[160:161], v[184:187], off nt
	v_lshl_add_u64 v[160:161], v[160:161], 0, s[46:47]
	v_pk_mul_f32 v[170:171], v[106:107], v[178:179] op_sel_hi:[1,0]
	v_pk_mul_f32 v[172:173], v[108:109], v[178:179] op_sel_hi:[1,0]
	v_pk_mul_f32 v[174:175], v[98:99], v[178:179] op_sel_hi:[1,0]
	v_pk_mul_f32 v[176:177], v[100:101], v[178:179] op_sel_hi:[1,0]
	v_exp_f32_e32 v170, v170
	v_exp_f32_e32 v171, v171
	v_exp_f32_e32 v172, v172
	v_exp_f32_e32 v173, v173
	v_exp_f32_e32 v174, v174
	v_exp_f32_e32 v175, v175
	v_exp_f32_e32 v176, v176
	v_exp_f32_e32 v177, v177
	v_pk_mul_f32 v[106:107], v[106:107], v[110:111]
	v_pk_mul_f32 v[108:109], v[108:109], v[112:113]
	v_pk_mul_f32 v[98:99], v[98:99], v[102:103]
	v_pk_mul_f32 v[100:101], v[100:101], v[104:105]
	v_pk_fma_f32 v[170:171], v[170:171], v[178:179], v[178:179] op_sel:[0,1,1] op_sel_hi:[1,1,1]
	v_pk_fma_f32 v[172:173], v[172:173], v[178:179], v[178:179] op_sel:[0,1,1] op_sel_hi:[1,1,1]
	v_pk_fma_f32 v[174:175], v[174:175], v[178:179], v[178:179] op_sel:[0,1,1] op_sel_hi:[1,1,1]
	v_pk_fma_f32 v[176:177], v[176:177], v[178:179], v[178:179] op_sel:[0,1,1] op_sel_hi:[1,1,1]
	v_rcp_f32_e32 v170, v170
	v_rcp_f32_e32 v171, v171
	v_rcp_f32_e32 v172, v172
	v_rcp_f32_e32 v173, v173
	v_rcp_f32_e32 v174, v174
	v_rcp_f32_e32 v175, v175
	v_rcp_f32_e32 v176, v176
	v_rcp_f32_e32 v177, v177
	s_waitcnt vmcnt(6)
	v_fmamk_f32 v167, v244, 0x3a800000, v194
	v_rsq_f32_e32 v166, v167
	s_nop 0
	v_mul_f32_e32 v166, 0xbfb8aa3b, v166
	v_pk_mul_f32 v[106:107], v[106:107], v[170:171]
	v_pk_mul_f32 v[108:109], v[108:109], v[172:173]
	v_pk_mul_f32 v[98:99], v[98:99], v[174:175]
	v_pk_mul_f32 v[100:101], v[100:101], v[176:177]
	v_cvt_pk_bf16_f32 v184, v106, v107
	v_cvt_pk_bf16_f32 v185, v108, v109
	v_cvt_pk_bf16_f32 v186, v98, v99
	v_cvt_pk_bf16_f32 v187, v100, v101
	global_store_dwordx4 v[160:161], v[184:187], off nt
	v_lshl_add_u64 v[160:161], v[160:161], 0, s[46:47]
	v_pk_mul_f32 v[170:171], v[90:91], v[166:167] op_sel_hi:[1,0]
	v_pk_mul_f32 v[172:173], v[92:93], v[166:167] op_sel_hi:[1,0]
	v_pk_mul_f32 v[174:175], v[82:83], v[166:167] op_sel_hi:[1,0]
	v_pk_mul_f32 v[176:177], v[84:85], v[166:167] op_sel_hi:[1,0]
	v_exp_f32_e32 v170, v170
	v_exp_f32_e32 v171, v171
	v_exp_f32_e32 v172, v172
	v_exp_f32_e32 v173, v173
	v_exp_f32_e32 v174, v174
	v_exp_f32_e32 v175, v175
	v_exp_f32_e32 v176, v176
	v_exp_f32_e32 v177, v177
	v_pk_mul_f32 v[90:91], v[90:91], v[94:95]
	v_pk_mul_f32 v[92:93], v[92:93], v[96:97]
	v_pk_mul_f32 v[82:83], v[82:83], v[86:87]
	v_pk_mul_f32 v[84:85], v[84:85], v[88:89]
	v_pk_fma_f32 v[170:171], v[170:171], v[166:167], v[166:167] op_sel:[0,1,1] op_sel_hi:[1,1,1]
	v_pk_fma_f32 v[172:173], v[172:173], v[166:167], v[166:167] op_sel:[0,1,1] op_sel_hi:[1,1,1]
	v_pk_fma_f32 v[174:175], v[174:175], v[166:167], v[166:167] op_sel:[0,1,1] op_sel_hi:[1,1,1]
	v_pk_fma_f32 v[176:177], v[176:177], v[166:167], v[166:167] op_sel:[0,1,1] op_sel_hi:[1,1,1]
	v_rcp_f32_e32 v170, v170
	v_rcp_f32_e32 v171, v171
	v_rcp_f32_e32 v172, v172
	v_rcp_f32_e32 v173, v173
	v_rcp_f32_e32 v174, v174
	v_rcp_f32_e32 v175, v175
	v_rcp_f32_e32 v176, v176
	v_rcp_f32_e32 v177, v177
	s_waitcnt vmcnt(6)
	v_fmamk_f32 v179, v245, 0x3a800000, v194
	v_rsq_f32_e32 v178, v179
	s_nop 0
	v_mul_f32_e32 v178, 0xbfb8aa3b, v178
	v_pk_mul_f32 v[90:91], v[90:91], v[170:171]
	v_pk_mul_f32 v[92:93], v[92:93], v[172:173]
	v_pk_mul_f32 v[82:83], v[82:83], v[174:175]
	v_pk_mul_f32 v[84:85], v[84:85], v[176:177]
	v_cvt_pk_bf16_f32 v184, v90, v91
	v_cvt_pk_bf16_f32 v185, v92, v93
	v_cvt_pk_bf16_f32 v186, v82, v83
	v_cvt_pk_bf16_f32 v187, v84, v85
	global_store_dwordx4 v[160:161], v[184:187], off nt
	v_lshl_add_u64 v[160:161], v[160:161], 0, s[46:47]
	v_pk_mul_f32 v[170:171], v[68:69], v[178:179] op_sel_hi:[1,0]
	v_pk_mul_f32 v[172:173], v[70:71], v[178:179] op_sel_hi:[1,0]
	v_pk_mul_f32 v[174:175], v[64:65], v[178:179] op_sel_hi:[1,0]
	v_pk_mul_f32 v[176:177], v[66:67], v[178:179] op_sel_hi:[1,0]
	v_exp_f32_e32 v170, v170
	v_exp_f32_e32 v171, v171
	v_exp_f32_e32 v172, v172
	v_exp_f32_e32 v173, v173
	v_exp_f32_e32 v174, v174
	v_exp_f32_e32 v175, v175
	v_exp_f32_e32 v176, v176
	v_exp_f32_e32 v177, v177
	v_pk_mul_f32 v[68:69], v[68:69], v[76:77]
	v_pk_mul_f32 v[70:71], v[70:71], v[78:79]
	v_pk_mul_f32 v[64:65], v[64:65], v[72:73]
	v_pk_mul_f32 v[66:67], v[66:67], v[74:75]
	v_pk_fma_f32 v[170:171], v[170:171], v[178:179], v[178:179] op_sel:[0,1,1] op_sel_hi:[1,1,1]
	v_pk_fma_f32 v[172:173], v[172:173], v[178:179], v[178:179] op_sel:[0,1,1] op_sel_hi:[1,1,1]
	v_pk_fma_f32 v[174:175], v[174:175], v[178:179], v[178:179] op_sel:[0,1,1] op_sel_hi:[1,1,1]
	v_pk_fma_f32 v[176:177], v[176:177], v[178:179], v[178:179] op_sel:[0,1,1] op_sel_hi:[1,1,1]
	v_rcp_f32_e32 v170, v170
	v_rcp_f32_e32 v171, v171
	v_rcp_f32_e32 v172, v172
	v_rcp_f32_e32 v173, v173
	v_rcp_f32_e32 v174, v174
	v_rcp_f32_e32 v175, v175
	v_rcp_f32_e32 v176, v176
	v_rcp_f32_e32 v177, v177
	s_waitcnt vmcnt(6)
	v_fmamk_f32 v167, v246, 0x3a800000, v194
	v_rsq_f32_e32 v166, v167
	s_nop 0
	v_mul_f32_e32 v166, 0xbfb8aa3b, v166
	v_pk_mul_f32 v[68:69], v[68:69], v[170:171]
	v_pk_mul_f32 v[70:71], v[70:71], v[172:173]
	v_pk_mul_f32 v[64:65], v[64:65], v[174:175]
	v_pk_mul_f32 v[66:67], v[66:67], v[176:177]
	v_cvt_pk_bf16_f32 v184, v68, v69
	v_cvt_pk_bf16_f32 v185, v70, v71
	v_cvt_pk_bf16_f32 v186, v64, v65
	v_cvt_pk_bf16_f32 v187, v66, v67
	global_store_dwordx4 v[160:161], v[184:187], off nt
	s_mov_b64 s[46:47], 0x6e000
	v_lshl_add_u64 v[160:161], v[160:161], 0, s[46:47]
	s_mov_b64 s[46:47], 0x16000
	v_pk_mul_f32 v[170:171], v[52:53], v[166:167] op_sel_hi:[1,0]
	v_pk_mul_f32 v[172:173], v[54:55], v[166:167] op_sel_hi:[1,0]
	v_pk_mul_f32 v[174:175], v[48:49], v[166:167] op_sel_hi:[1,0]
	v_pk_mul_f32 v[176:177], v[50:51], v[166:167] op_sel_hi:[1,0]
	v_exp_f32_e32 v170, v170
	v_exp_f32_e32 v171, v171
	v_exp_f32_e32 v172, v172
	v_exp_f32_e32 v173, v173
	v_exp_f32_e32 v174, v174
	v_exp_f32_e32 v175, v175
	v_exp_f32_e32 v176, v176
	v_exp_f32_e32 v177, v177
	v_pk_mul_f32 v[52:53], v[52:53], v[60:61]
	v_pk_mul_f32 v[54:55], v[54:55], v[62:63]
	v_pk_mul_f32 v[48:49], v[48:49], v[56:57]
	v_pk_mul_f32 v[50:51], v[50:51], v[58:59]
	v_pk_fma_f32 v[170:171], v[170:171], v[166:167], v[166:167] op_sel:[0,1,1] op_sel_hi:[1,1,1]
	v_pk_fma_f32 v[172:173], v[172:173], v[166:167], v[166:167] op_sel:[0,1,1] op_sel_hi:[1,1,1]
	v_pk_fma_f32 v[174:175], v[174:175], v[166:167], v[166:167] op_sel:[0,1,1] op_sel_hi:[1,1,1]
	v_pk_fma_f32 v[176:177], v[176:177], v[166:167], v[166:167] op_sel:[0,1,1] op_sel_hi:[1,1,1]
	v_rcp_f32_e32 v170, v170
	v_rcp_f32_e32 v171, v171
	v_rcp_f32_e32 v172, v172
	v_rcp_f32_e32 v173, v173
	v_rcp_f32_e32 v174, v174
	v_rcp_f32_e32 v175, v175
	v_rcp_f32_e32 v176, v176
	v_rcp_f32_e32 v177, v177
	s_waitcnt vmcnt(6)
	v_fmamk_f32 v179, v247, 0x3a800000, v194
	v_rsq_f32_e32 v178, v179
	s_nop 0
	v_mul_f32_e32 v178, 0xbfb8aa3b, v178
	v_pk_mul_f32 v[52:53], v[52:53], v[170:171]
	v_pk_mul_f32 v[54:55], v[54:55], v[172:173]
	v_pk_mul_f32 v[48:49], v[48:49], v[174:175]
	v_pk_mul_f32 v[50:51], v[50:51], v[176:177]
	v_cvt_pk_bf16_f32 v184, v52, v53
	v_cvt_pk_bf16_f32 v185, v54, v55
	v_cvt_pk_bf16_f32 v186, v48, v49
	v_cvt_pk_bf16_f32 v187, v50, v51
	global_store_dwordx4 v[160:161], v[184:187], off nt
	v_lshl_add_u64 v[160:161], v[160:161], 0, s[46:47]
	v_pk_mul_f32 v[170:171], v[36:37], v[178:179] op_sel_hi:[1,0]
	v_pk_mul_f32 v[172:173], v[38:39], v[178:179] op_sel_hi:[1,0]
	v_pk_mul_f32 v[174:175], v[32:33], v[178:179] op_sel_hi:[1,0]
	v_pk_mul_f32 v[176:177], v[34:35], v[178:179] op_sel_hi:[1,0]
	v_exp_f32_e32 v170, v170
	v_exp_f32_e32 v171, v171
	v_exp_f32_e32 v172, v172
	v_exp_f32_e32 v173, v173
	v_exp_f32_e32 v174, v174
	v_exp_f32_e32 v175, v175
	v_exp_f32_e32 v176, v176
	v_exp_f32_e32 v177, v177
	v_pk_mul_f32 v[36:37], v[36:37], v[44:45]
	v_pk_mul_f32 v[38:39], v[38:39], v[46:47]
	v_pk_mul_f32 v[32:33], v[32:33], v[40:41]
	v_pk_mul_f32 v[34:35], v[34:35], v[42:43]
	v_pk_fma_f32 v[170:171], v[170:171], v[178:179], v[178:179] op_sel:[0,1,1] op_sel_hi:[1,1,1]
	v_pk_fma_f32 v[172:173], v[172:173], v[178:179], v[178:179] op_sel:[0,1,1] op_sel_hi:[1,1,1]
	v_pk_fma_f32 v[174:175], v[174:175], v[178:179], v[178:179] op_sel:[0,1,1] op_sel_hi:[1,1,1]
	v_pk_fma_f32 v[176:177], v[176:177], v[178:179], v[178:179] op_sel:[0,1,1] op_sel_hi:[1,1,1]
	v_rcp_f32_e32 v170, v170
	v_rcp_f32_e32 v171, v171
	v_rcp_f32_e32 v172, v172
	v_rcp_f32_e32 v173, v173
	v_rcp_f32_e32 v174, v174
	v_rcp_f32_e32 v175, v175
	v_rcp_f32_e32 v176, v176
	v_rcp_f32_e32 v177, v177
	s_waitcnt vmcnt(6)
	v_fmamk_f32 v167, v248, 0x3a800000, v194
	v_rsq_f32_e32 v166, v167
	s_nop 0
	v_mul_f32_e32 v166, 0xbfb8aa3b, v166
	v_pk_mul_f32 v[36:37], v[36:37], v[170:171]
	v_pk_mul_f32 v[38:39], v[38:39], v[172:173]
	v_pk_mul_f32 v[32:33], v[32:33], v[174:175]
	v_pk_mul_f32 v[34:35], v[34:35], v[176:177]
	v_cvt_pk_bf16_f32 v184, v36, v37
	v_cvt_pk_bf16_f32 v185, v38, v39
	v_cvt_pk_bf16_f32 v186, v32, v33
	v_cvt_pk_bf16_f32 v187, v34, v35
	global_store_dwordx4 v[160:161], v[184:187], off nt
	v_lshl_add_u64 v[160:161], v[160:161], 0, s[46:47]
	v_pk_mul_f32 v[170:171], v[20:21], v[166:167] op_sel_hi:[1,0]
	v_pk_mul_f32 v[172:173], v[22:23], v[166:167] op_sel_hi:[1,0]
	v_pk_mul_f32 v[174:175], v[16:17], v[166:167] op_sel_hi:[1,0]
	v_pk_mul_f32 v[176:177], v[18:19], v[166:167] op_sel_hi:[1,0]
	v_exp_f32_e32 v170, v170
	v_exp_f32_e32 v171, v171
	v_exp_f32_e32 v172, v172
	v_exp_f32_e32 v173, v173
	v_exp_f32_e32 v174, v174
	v_exp_f32_e32 v175, v175
	v_exp_f32_e32 v176, v176
	v_exp_f32_e32 v177, v177
	v_pk_mul_f32 v[20:21], v[20:21], v[28:29]
	v_pk_mul_f32 v[22:23], v[22:23], v[30:31]
	v_pk_mul_f32 v[16:17], v[16:17], v[24:25]
	v_pk_mul_f32 v[18:19], v[18:19], v[26:27]
	v_pk_fma_f32 v[170:171], v[170:171], v[166:167], v[166:167] op_sel:[0,1,1] op_sel_hi:[1,1,1]
	v_pk_fma_f32 v[172:173], v[172:173], v[166:167], v[166:167] op_sel:[0,1,1] op_sel_hi:[1,1,1]
	v_pk_fma_f32 v[174:175], v[174:175], v[166:167], v[166:167] op_sel:[0,1,1] op_sel_hi:[1,1,1]
	v_pk_fma_f32 v[176:177], v[176:177], v[166:167], v[166:167] op_sel:[0,1,1] op_sel_hi:[1,1,1]
	v_rcp_f32_e32 v170, v170
	v_rcp_f32_e32 v171, v171
	v_rcp_f32_e32 v172, v172
	v_rcp_f32_e32 v173, v173
	v_rcp_f32_e32 v174, v174
	v_rcp_f32_e32 v175, v175
	v_rcp_f32_e32 v176, v176
	v_rcp_f32_e32 v177, v177
	s_waitcnt vmcnt(6)
	v_fmamk_f32 v179, v249, 0x3a800000, v194
	v_rsq_f32_e32 v178, v179
	s_nop 0
	v_mul_f32_e32 v178, 0xbfb8aa3b, v178
	v_pk_mul_f32 v[20:21], v[20:21], v[170:171]
	v_pk_mul_f32 v[22:23], v[22:23], v[172:173]
	v_pk_mul_f32 v[16:17], v[16:17], v[174:175]
	v_pk_mul_f32 v[18:19], v[18:19], v[176:177]
	v_cvt_pk_bf16_f32 v184, v20, v21
	v_cvt_pk_bf16_f32 v185, v22, v23
	v_cvt_pk_bf16_f32 v186, v16, v17
	v_cvt_pk_bf16_f32 v187, v18, v19
	global_store_dwordx4 v[160:161], v[184:187], off nt
	v_lshl_add_u64 v[160:161], v[160:161], 0, s[46:47]
	v_pk_mul_f32 v[170:171], v[8:9], v[178:179] op_sel_hi:[1,0]
	v_pk_mul_f32 v[172:173], v[10:11], v[178:179] op_sel_hi:[1,0]
	v_pk_mul_f32 v[174:175], v[0:1], v[178:179] op_sel_hi:[1,0]
	v_pk_mul_f32 v[176:177], v[2:3], v[178:179] op_sel_hi:[1,0]
	v_exp_f32_e32 v170, v170
	v_exp_f32_e32 v171, v171
	v_exp_f32_e32 v172, v172
	v_exp_f32_e32 v173, v173
	v_exp_f32_e32 v174, v174
	v_exp_f32_e32 v175, v175
	v_exp_f32_e32 v176, v176
	v_exp_f32_e32 v177, v177
	v_pk_mul_f32 v[8:9], v[8:9], v[12:13]
	v_pk_mul_f32 v[10:11], v[10:11], v[14:15]
	v_pk_mul_f32 v[0:1], v[0:1], v[4:5]
	v_pk_mul_f32 v[2:3], v[2:3], v[6:7]
	v_pk_fma_f32 v[170:171], v[170:171], v[178:179], v[178:179] op_sel:[0,1,1] op_sel_hi:[1,1,1]
	v_pk_fma_f32 v[172:173], v[172:173], v[178:179], v[178:179] op_sel:[0,1,1] op_sel_hi:[1,1,1]
	v_pk_fma_f32 v[174:175], v[174:175], v[178:179], v[178:179] op_sel:[0,1,1] op_sel_hi:[1,1,1]
	v_pk_fma_f32 v[176:177], v[176:177], v[178:179], v[178:179] op_sel:[0,1,1] op_sel_hi:[1,1,1]
	v_rcp_f32_e32 v170, v170
	v_rcp_f32_e32 v171, v171
	v_rcp_f32_e32 v172, v172
	v_rcp_f32_e32 v173, v173
	v_rcp_f32_e32 v174, v174
	v_rcp_f32_e32 v175, v175
	v_rcp_f32_e32 v176, v176
	v_rcp_f32_e32 v177, v177
	v_pk_mul_f32 v[8:9], v[8:9], v[170:171]
	v_pk_mul_f32 v[10:11], v[10:11], v[172:173]
	v_pk_mul_f32 v[0:1], v[0:1], v[174:175]
	v_pk_mul_f32 v[2:3], v[2:3], v[176:177]
	v_cvt_pk_bf16_f32 v184, v8, v9
	v_cvt_pk_bf16_f32 v185, v10, v11
	v_cvt_pk_bf16_f32 v186, v0, v1
	v_cvt_pk_bf16_f32 v187, v2, v3
	global_store_dwordx4 v[160:161], v[184:187], off nt
	s_andn2_b64 vcc, exec, s[44:45]
	s_mov_b64 s[44:45], -1
	s_cbranch_vccnz .LBB0_223
	s_andn2_b64 vcc, exec, s[0:1]
	s_cbranch_vccnz .LBB0_222
	s_barrier
	s_branch .LBB0_222

.Lsw1_go:
	s_mov_b64 s[46:47], 0x16000
	s_waitcnt vmcnt(7)
	v_fmamk_f32 v167, v242, 0x3a800000, v194
	v_rsq_f32_e32 v166, v167
	s_nop 0
	v_mul_f32_e32 v166, 0xbfb8aa3b, v166
	v_pk_mul_f32 v[170:171], v[126:127], v[166:167] op_sel_hi:[1,0]
	v_pk_mul_f32 v[172:173], v[128:129], v[166:167] op_sel_hi:[1,0]
	v_pk_mul_f32 v[174:175], v[118:119], v[166:167] op_sel_hi:[1,0]
	v_pk_mul_f32 v[176:177], v[120:121], v[166:167] op_sel_hi:[1,0]
	v_exp_f32_e32 v170, v170
	v_exp_f32_e32 v171, v171
	v_exp_f32_e32 v172, v172
	v_exp_f32_e32 v173, v173
	v_exp_f32_e32 v174, v174
	v_exp_f32_e32 v175, v175
	v_exp_f32_e32 v176, v176
	v_exp_f32_e32 v177, v177
	v_pk_mul_f32 v[126:127], v[126:127], v[122:123]
	v_pk_mul_f32 v[128:129], v[128:129], v[124:125]
	v_pk_mul_f32 v[118:119], v[118:119], v[114:115]
	v_pk_mul_f32 v[120:121], v[120:121], v[116:117]
	v_pk_fma_f32 v[170:171], v[170:171], v[166:167], v[166:167] op_sel:[0,1,1] op_sel_hi:[1,1,1]
	v_pk_fma_f32 v[172:173], v[172:173], v[166:167], v[166:167] op_sel:[0,1,1] op_sel_hi:[1,1,1]
	v_pk_fma_f32 v[174:175], v[174:175], v[166:167], v[166:167] op_sel:[0,1,1] op_sel_hi:[1,1,1]
	v_pk_fma_f32 v[176:177], v[176:177], v[166:167], v[166:167] op_sel:[0,1,1] op_sel_hi:[1,1,1]
	v_rcp_f32_e32 v170, v170
	v_rcp_f32_e32 v171, v171
	v_rcp_f32_e32 v172, v172
	v_rcp_f32_e32 v173, v173
	v_rcp_f32_e32 v174, v174
	v_rcp_f32_e32 v175, v175
	v_rcp_f32_e32 v176, v176
	v_rcp_f32_e32 v177, v177
	s_waitcnt vmcnt(6)
	v_fmamk_f32 v179, v243, 0x3a800000, v194
	v_rsq_f32_e32 v178, v179
	s_nop 0
	v_mul_f32_e32 v178, 0xbfb8aa3b, v178
	v_pk_mul_f32 v[126:127], v[126:127], v[170:171]
	v_pk_mul_f32 v[128:129], v[128:129], v[172:173]
	v_pk_mul_f32 v[118:119], v[118:119], v[174:175]
	v_pk_mul_f32 v[120:121], v[120:121], v[176:177]
	v_cvt_pk_bf16_f32 v184, v126, v127
	v_cvt_pk_bf16_f32 v185, v128, v129
	v_cvt_pk_bf16_f32 v186, v118, v119
	v_cvt_pk_bf16_f32 v187, v120, v121
	global_store_dwordx4 v[160:161], v[184:187], off nt
	v_lshl_add_u64 v[160:161], v[160:161], 0, s[46:47]
	v_pk_mul_f32 v[170:171], v[110:111], v[178:179] op_sel_hi:[1,0]
	v_pk_mul_f32 v[172:173], v[112:113], v[178:179] op_sel_hi:[1,0]
	v_pk_mul_f32 v[174:175], v[102:103], v[178:179] op_sel_hi:[1,0]
	v_pk_mul_f32 v[176:177], v[104:105], v[178:179] op_sel_hi:[1,0]
	v_exp_f32_e32 v170, v170
	v_exp_f32_e32 v171, v171
	v_exp_f32_e32 v172, v172
	v_exp_f32_e32 v173, v173
	v_exp_f32_e32 v174, v174
	v_exp_f32_e32 v175, v175
	v_exp_f32_e32 v176, v176
	v_exp_f32_e32 v177, v177
	v_pk_mul_f32 v[110:111], v[110:111], v[106:107]
	v_pk_mul_f32 v[112:113], v[112:113], v[108:109]
	v_pk_mul_f32 v[102:103], v[102:103], v[98:99]
	v_pk_mul_f32 v[104:105], v[104:105], v[100:101]
	v_pk_fma_f32 v[170:171], v[170:171], v[178:179], v[178:179] op_sel:[0,1,1] op_sel_hi:[1,1,1]
	v_pk_fma_f32 v[172:173], v[172:173], v[178:179], v[178:179] op_sel:[0,1,1] op_sel_hi:[1,1,1]
	v_pk_fma_f32 v[174:175], v[174:175], v[178:179], v[178:179] op_sel:[0,1,1] op_sel_hi:[1,1,1]
	v_pk_fma_f32 v[176:177], v[176:177], v[178:179], v[178:179] op_sel:[0,1,1] op_sel_hi:[1,1,1]
	v_rcp_f32_e32 v170, v170
	v_rcp_f32_e32 v171, v171
	v_rcp_f32_e32 v172, v172
	v_rcp_f32_e32 v173, v173
	v_rcp_f32_e32 v174, v174
	v_rcp_f32_e32 v175, v175
	v_rcp_f32_e32 v176, v176
	v_rcp_f32_e32 v177, v177
	s_waitcnt vmcnt(6)
	v_fmamk_f32 v167, v244, 0x3a800000, v194
	v_rsq_f32_e32 v166, v167
	s_nop 0
	v_mul_f32_e32 v166, 0xbfb8aa3b, v166
	v_pk_mul_f32 v[110:111], v[110:111], v[170:171]
	v_pk_mul_f32 v[112:113], v[112:113], v[172:173]
	v_pk_mul_f32 v[102:103], v[102:103], v[174:175]
	v_pk_mul_f32 v[104:105], v[104:105], v[176:177]
	v_cvt_pk_bf16_f32 v184, v110, v111
	v_cvt_pk_bf16_f32 v185, v112, v113
	v_cvt_pk_bf16_f32 v186, v102, v103
	v_cvt_pk_bf16_f32 v187, v104, v105
	global_store_dwordx4 v[160:161], v[184:187], off nt
	v_lshl_add_u64 v[160:161], v[160:161], 0, s[46:47]
	v_pk_mul_f32 v[170:171], v[94:95], v[166:167] op_sel_hi:[1,0]
	v_pk_mul_f32 v[172:173], v[96:97], v[166:167] op_sel_hi:[1,0]
	v_pk_mul_f32 v[174:175], v[86:87], v[166:167] op_sel_hi:[1,0]
	v_pk_mul_f32 v[176:177], v[88:89], v[166:167] op_sel_hi:[1,0]
	v_exp_f32_e32 v170, v170
	v_exp_f32_e32 v171, v171
	v_exp_f32_e32 v172, v172
	v_exp_f32_e32 v173, v173
	v_exp_f32_e32 v174, v174
	v_exp_f32_e32 v175, v175
	v_exp_f32_e32 v176, v176
	v_exp_f32_e32 v177, v177
	v_pk_mul_f32 v[94:95], v[94:95], v[90:91]
	v_pk_mul_f32 v[96:97], v[96:97], v[92:93]
	v_pk_mul_f32 v[86:87], v[86:87], v[82:83]
	v_pk_mul_f32 v[88:89], v[88:89], v[84:85]
	v_pk_fma_f32 v[170:171], v[170:171], v[166:167], v[166:167] op_sel:[0,1,1] op_sel_hi:[1,1,1]
	v_pk_fma_f32 v[172:173], v[172:173], v[166:167], v[166:167] op_sel:[0,1,1] op_sel_hi:[1,1,1]
	v_pk_fma_f32 v[174:175], v[174:175], v[166:167], v[166:167] op_sel:[0,1,1] op_sel_hi:[1,1,1]
	v_pk_fma_f32 v[176:177], v[176:177], v[166:167], v[166:167] op_sel:[0,1,1] op_sel_hi:[1,1,1]
	v_rcp_f32_e32 v170, v170
	v_rcp_f32_e32 v171, v171
	v_rcp_f32_e32 v172, v172
	v_rcp_f32_e32 v173, v173
	v_rcp_f32_e32 v174, v174
	v_rcp_f32_e32 v175, v175
	v_rcp_f32_e32 v176, v176
	v_rcp_f32_e32 v177, v177
	s_waitcnt vmcnt(6)
	v_fmamk_f32 v179, v245, 0x3a800000, v194
	v_rsq_f32_e32 v178, v179
	s_nop 0
	v_mul_f32_e32 v178, 0xbfb8aa3b, v178
	v_pk_mul_f32 v[94:95], v[94:95], v[170:171]
	v_pk_mul_f32 v[96:97], v[96:97], v[172:173]
	v_pk_mul_f32 v[86:87], v[86:87], v[174:175]
	v_pk_mul_f32 v[88:89], v[88:89], v[176:177]
	v_cvt_pk_bf16_f32 v184, v94, v95
	v_cvt_pk_bf16_f32 v185, v96, v97
	v_cvt_pk_bf16_f32 v186, v86, v87
	v_cvt_pk_bf16_f32 v187, v88, v89
	global_store_dwordx4 v[160:161], v[184:187], off nt
	v_lshl_add_u64 v[160:161], v[160:161], 0, s[46:47]
	v_pk_mul_f32 v[170:171], v[76:77], v[178:179] op_sel_hi:[1,0]
	v_pk_mul_f32 v[172:173], v[78:79], v[178:179] op_sel_hi:[1,0]
	v_pk_mul_f32 v[174:175], v[68:69], v[178:179] op_sel_hi:[1,0]
	v_pk_mul_f32 v[176:177], v[70:71], v[178:179] op_sel_hi:[1,0]
	v_exp_f32_e32 v170, v170
	v_exp_f32_e32 v171, v171
	v_exp_f32_e32 v172, v172
	v_exp_f32_e32 v173, v173
	v_exp_f32_e32 v174, v174
	v_exp_f32_e32 v175, v175
	v_exp_f32_e32 v176, v176
	v_exp_f32_e32 v177, v177
	v_pk_mul_f32 v[76:77], v[76:77], v[72:73]
	v_pk_mul_f32 v[78:79], v[78:79], v[74:75]
	v_pk_mul_f32 v[68:69], v[68:69], v[64:65]
	v_pk_mul_f32 v[70:71], v[70:71], v[66:67]
	v_pk_fma_f32 v[170:171], v[170:171], v[178:179], v[178:179] op_sel:[0,1,1] op_sel_hi:[1,1,1]
	v_pk_fma_f32 v[172:173], v[172:173], v[178:179], v[178:179] op_sel:[0,1,1] op_sel_hi:[1,1,1]
	v_pk_fma_f32 v[174:175], v[174:175], v[178:179], v[178:179] op_sel:[0,1,1] op_sel_hi:[1,1,1]
	v_pk_fma_f32 v[176:177], v[176:177], v[178:179], v[178:179] op_sel:[0,1,1] op_sel_hi:[1,1,1]
	v_rcp_f32_e32 v170, v170
	v_rcp_f32_e32 v171, v171
	v_rcp_f32_e32 v172, v172
	v_rcp_f32_e32 v173, v173
	v_rcp_f32_e32 v174, v174
	v_rcp_f32_e32 v175, v175
	v_rcp_f32_e32 v176, v176
	v_rcp_f32_e32 v177, v177
	s_waitcnt vmcnt(6)
	v_fmamk_f32 v167, v246, 0x3a800000, v194
	v_rsq_f32_e32 v166, v167
	s_nop 0
	v_mul_f32_e32 v166, 0xbfb8aa3b, v166
	v_pk_mul_f32 v[76:77], v[76:77], v[170:171]
	v_pk_mul_f32 v[78:79], v[78:79], v[172:173]
	v_pk_mul_f32 v[68:69], v[68:69], v[174:175]
	v_pk_mul_f32 v[70:71], v[70:71], v[176:177]
	v_cvt_pk_bf16_f32 v184, v76, v77
	v_cvt_pk_bf16_f32 v185, v78, v79
	v_cvt_pk_bf16_f32 v186, v68, v69
	v_cvt_pk_bf16_f32 v187, v70, v71
	global_store_dwordx4 v[160:161], v[184:187], off nt
	s_mov_b64 s[46:47], 0x6e000
	v_lshl_add_u64 v[160:161], v[160:161], 0, s[46:47]
	s_mov_b64 s[46:47], 0x16000
	v_pk_mul_f32 v[170:171], v[60:61], v[166:167] op_sel_hi:[1,0]
	v_pk_mul_f32 v[172:173], v[62:63], v[166:167] op_sel_hi:[1,0]
	v_pk_mul_f32 v[174:175], v[52:53], v[166:167] op_sel_hi:[1,0]
	v_pk_mul_f32 v[176:177], v[54:55], v[166:167] op_sel_hi:[1,0]
	v_exp_f32_e32 v170, v170
	v_exp_f32_e32 v171, v171
	v_exp_f32_e32 v172, v172
	v_exp_f32_e32 v173, v173
	v_exp_f32_e32 v174, v174
	v_exp_f32_e32 v175, v175
	v_exp_f32_e32 v176, v176
	v_exp_f32_e32 v177, v177
	v_pk_mul_f32 v[60:61], v[60:61], v[56:57]
	v_pk_mul_f32 v[62:63], v[62:63], v[58:59]
	v_pk_mul_f32 v[52:53], v[52:53], v[48:49]
	v_pk_mul_f32 v[54:55], v[54:55], v[50:51]
	v_pk_fma_f32 v[170:171], v[170:171], v[166:167], v[166:167] op_sel:[0,1,1] op_sel_hi:[1,1,1]
	v_pk_fma_f32 v[172:173], v[172:173], v[166:167], v[166:167] op_sel:[0,1,1] op_sel_hi:[1,1,1]
	v_pk_fma_f32 v[174:175], v[174:175], v[166:167], v[166:167] op_sel:[0,1,1] op_sel_hi:[1,1,1]
	v_pk_fma_f32 v[176:177], v[176:177], v[166:167], v[166:167] op_sel:[0,1,1] op_sel_hi:[1,1,1]
	v_rcp_f32_e32 v170, v170
	v_rcp_f32_e32 v171, v171
	v_rcp_f32_e32 v172, v172
	v_rcp_f32_e32 v173, v173
	v_rcp_f32_e32 v174, v174
	v_rcp_f32_e32 v175, v175
	v_rcp_f32_e32 v176, v176
	v_rcp_f32_e32 v177, v177
	s_waitcnt vmcnt(6)
	v_fmamk_f32 v179, v247, 0x3a800000, v194
	v_rsq_f32_e32 v178, v179
	s_nop 0
	v_mul_f32_e32 v178, 0xbfb8aa3b, v178
	v_pk_mul_f32 v[60:61], v[60:61], v[170:171]
	v_pk_mul_f32 v[62:63], v[62:63], v[172:173]
	v_pk_mul_f32 v[52:53], v[52:53], v[174:175]
	v_pk_mul_f32 v[54:55], v[54:55], v[176:177]
	v_cvt_pk_bf16_f32 v184, v60, v61
	v_cvt_pk_bf16_f32 v185, v62, v63
	v_cvt_pk_bf16_f32 v186, v52, v53
	v_cvt_pk_bf16_f32 v187, v54, v55
	global_store_dwordx4 v[160:161], v[184:187], off nt
	v_lshl_add_u64 v[160:161], v[160:161], 0, s[46:47]
	v_pk_mul_f32 v[170:171], v[44:45], v[178:179] op_sel_hi:[1,0]
	v_pk_mul_f32 v[172:173], v[46:47], v[178:179] op_sel_hi:[1,0]
	v_pk_mul_f32 v[174:175], v[36:37], v[178:179] op_sel_hi:[1,0]
	v_pk_mul_f32 v[176:177], v[38:39], v[178:179] op_sel_hi:[1,0]
	v_exp_f32_e32 v170, v170
	v_exp_f32_e32 v171, v171
	v_exp_f32_e32 v172, v172
	v_exp_f32_e32 v173, v173
	v_exp_f32_e32 v174, v174
	v_exp_f32_e32 v175, v175
	v_exp_f32_e32 v176, v176
	v_exp_f32_e32 v177, v177
	v_pk_mul_f32 v[44:45], v[44:45], v[40:41]
	v_pk_mul_f32 v[46:47], v[46:47], v[42:43]
	v_pk_mul_f32 v[36:37], v[36:37], v[32:33]
	v_pk_mul_f32 v[38:39], v[38:39], v[34:35]
	v_pk_fma_f32 v[170:171], v[170:171], v[178:179], v[178:179] op_sel:[0,1,1] op_sel_hi:[1,1,1]
	v_pk_fma_f32 v[172:173], v[172:173], v[178:179], v[178:179] op_sel:[0,1,1] op_sel_hi:[1,1,1]
	v_pk_fma_f32 v[174:175], v[174:175], v[178:179], v[178:179] op_sel:[0,1,1] op_sel_hi:[1,1,1]
	v_pk_fma_f32 v[176:177], v[176:177], v[178:179], v[178:179] op_sel:[0,1,1] op_sel_hi:[1,1,1]
	v_rcp_f32_e32 v170, v170
	v_rcp_f32_e32 v171, v171
	v_rcp_f32_e32 v172, v172
	v_rcp_f32_e32 v173, v173
	v_rcp_f32_e32 v174, v174
	v_rcp_f32_e32 v175, v175
	v_rcp_f32_e32 v176, v176
	v_rcp_f32_e32 v177, v177
	s_waitcnt vmcnt(6)
	v_fmamk_f32 v167, v248, 0x3a800000, v194
	v_rsq_f32_e32 v166, v167
	s_nop 0
	v_mul_f32_e32 v166, 0xbfb8aa3b, v166
	v_pk_mul_f32 v[44:45], v[44:45], v[170:171]
	v_pk_mul_f32 v[46:47], v[46:47], v[172:173]
	v_pk_mul_f32 v[36:37], v[36:37], v[174:175]
	v_pk_mul_f32 v[38:39], v[38:39], v[176:177]
	v_cvt_pk_bf16_f32 v184, v44, v45
	v_cvt_pk_bf16_f32 v185, v46, v47
	v_cvt_pk_bf16_f32 v186, v36, v37
	v_cvt_pk_bf16_f32 v187, v38, v39
	global_store_dwordx4 v[160:161], v[184:187], off nt
	v_lshl_add_u64 v[160:161], v[160:161], 0, s[46:47]
	v_pk_mul_f32 v[170:171], v[28:29], v[166:167] op_sel_hi:[1,0]
	v_pk_mul_f32 v[172:173], v[30:31], v[166:167] op_sel_hi:[1,0]
	v_pk_mul_f32 v[174:175], v[20:21], v[166:167] op_sel_hi:[1,0]
	v_pk_mul_f32 v[176:177], v[22:23], v[166:167] op_sel_hi:[1,0]
	v_exp_f32_e32 v170, v170
	v_exp_f32_e32 v171, v171
	v_exp_f32_e32 v172, v172
	v_exp_f32_e32 v173, v173
	v_exp_f32_e32 v174, v174
	v_exp_f32_e32 v175, v175
	v_exp_f32_e32 v176, v176
	v_exp_f32_e32 v177, v177
	v_pk_mul_f32 v[28:29], v[28:29], v[24:25]
	v_pk_mul_f32 v[30:31], v[30:31], v[26:27]
	v_pk_mul_f32 v[20:21], v[20:21], v[16:17]
	v_pk_mul_f32 v[22:23], v[22:23], v[18:19]
	v_pk_fma_f32 v[170:171], v[170:171], v[166:167], v[166:167] op_sel:[0,1,1] op_sel_hi:[1,1,1]
	v_pk_fma_f32 v[172:173], v[172:173], v[166:167], v[166:167] op_sel:[0,1,1] op_sel_hi:[1,1,1]
	v_pk_fma_f32 v[174:175], v[174:175], v[166:167], v[166:167] op_sel:[0,1,1] op_sel_hi:[1,1,1]
	v_pk_fma_f32 v[176:177], v[176:177], v[166:167], v[166:167] op_sel:[0,1,1] op_sel_hi:[1,1,1]
	v_rcp_f32_e32 v170, v170
	v_rcp_f32_e32 v171, v171
	v_rcp_f32_e32 v172, v172
	v_rcp_f32_e32 v173, v173
	v_rcp_f32_e32 v174, v174
	v_rcp_f32_e32 v175, v175
	v_rcp_f32_e32 v176, v176
	v_rcp_f32_e32 v177, v177
	s_waitcnt vmcnt(6)
	v_fmamk_f32 v179, v249, 0x3a800000, v194
	v_rsq_f32_e32 v178, v179
	s_nop 0
	v_mul_f32_e32 v178, 0xbfb8aa3b, v178
	v_pk_mul_f32 v[28:29], v[28:29], v[170:171]
	v_pk_mul_f32 v[30:31], v[30:31], v[172:173]
	v_pk_mul_f32 v[20:21], v[20:21], v[174:175]
	v_pk_mul_f32 v[22:23], v[22:23], v[176:177]
	v_cvt_pk_bf16_f32 v184, v28, v29
	v_cvt_pk_bf16_f32 v185, v30, v31
	v_cvt_pk_bf16_f32 v186, v20, v21
	v_cvt_pk_bf16_f32 v187, v22, v23
	global_store_dwordx4 v[160:161], v[184:187], off nt
	v_lshl_add_u64 v[160:161], v[160:161], 0, s[46:47]
	v_pk_mul_f32 v[170:171], v[12:13], v[178:179] op_sel_hi:[1,0]
	v_pk_mul_f32 v[172:173], v[14:15], v[178:179] op_sel_hi:[1,0]
	v_pk_mul_f32 v[174:175], v[4:5], v[178:179] op_sel_hi:[1,0]
	v_pk_mul_f32 v[176:177], v[6:7], v[178:179] op_sel_hi:[1,0]
	v_exp_f32_e32 v170, v170
	v_exp_f32_e32 v171, v171
	v_exp_f32_e32 v172, v172
	v_exp_f32_e32 v173, v173
	v_exp_f32_e32 v174, v174
	v_exp_f32_e32 v175, v175
	v_exp_f32_e32 v176, v176
	v_exp_f32_e32 v177, v177
	v_pk_mul_f32 v[12:13], v[12:13], v[8:9]
	v_pk_mul_f32 v[14:15], v[14:15], v[10:11]
	v_pk_mul_f32 v[4:5], v[4:5], v[0:1]
	v_pk_mul_f32 v[6:7], v[6:7], v[2:3]
	v_pk_fma_f32 v[170:171], v[170:171], v[178:179], v[178:179] op_sel:[0,1,1] op_sel_hi:[1,1,1]
	v_pk_fma_f32 v[172:173], v[172:173], v[178:179], v[178:179] op_sel:[0,1,1] op_sel_hi:[1,1,1]
	v_pk_fma_f32 v[174:175], v[174:175], v[178:179], v[178:179] op_sel:[0,1,1] op_sel_hi:[1,1,1]
	v_pk_fma_f32 v[176:177], v[176:177], v[178:179], v[178:179] op_sel:[0,1,1] op_sel_hi:[1,1,1]
	v_rcp_f32_e32 v170, v170
	v_rcp_f32_e32 v171, v171
	v_rcp_f32_e32 v172, v172
	v_rcp_f32_e32 v173, v173
	v_rcp_f32_e32 v174, v174
	v_rcp_f32_e32 v175, v175
	v_rcp_f32_e32 v176, v176
	v_rcp_f32_e32 v177, v177
	v_pk_mul_f32 v[12:13], v[12:13], v[170:171]
	v_pk_mul_f32 v[14:15], v[14:15], v[172:173]
	v_pk_mul_f32 v[4:5], v[4:5], v[174:175]
	v_pk_mul_f32 v[6:7], v[6:7], v[176:177]
	v_cvt_pk_bf16_f32 v184, v12, v13
	v_cvt_pk_bf16_f32 v185, v14, v15
	v_cvt_pk_bf16_f32 v186, v4, v5
	v_cvt_pk_bf16_f32 v187, v6, v7
	global_store_dwordx4 v[160:161], v[184:187], off nt
	s_andn2_b64 vcc, exec, s[40:41]
	s_mov_b64 s[46:47], -1
	s_cbranch_vccnz .LBB0_673
	s_andn2_b64 vcc, exec, s[0:1]
	s_cbranch_vccnz .LBB0_672
	s_barrier
	s_branch .LBB0_672
